# v101 (no redundant setprio pairs) plus the 8 WA staging loads of the P0 prologue issued up front with counted waits
# speedup vs baseline: 1.0035x; 1.0035x over previous
; __device__ __forceinline__ unsigned pk2(float lo, float hi) { return pg8::cvt_pk_bf16(lo, hi); }
; __device__ __forceinline__ void p0_prologue(const Ptrs& P, LAS unsigned char* lds, int tid, int G, int blk) {
;     ...
;     for (int idx = tid; idx < 4096; idx += 512) { const int k = idx >> 2, c = (idx & 3) * 4; const f32x4 w = *(const f32x4*)(P.w_in + (size_t)k * 6672 + 3072 + c); const unsigned p0 = pk2(w.x, w.y), p1 = pk2(w.z, w.w);
;         WA[(c + 0) * 1032 + k] = (bf16_t)(p0 & 0xffffu); WA[(c + 1) * 1032 + k] = (bf16_t)(p0 >> 16); WA[(c + 2) * 1032 + k] = (bf16_t)(p1 & 0xffffu); WA[(c + 3) * 1032 + k] = (bf16_t)(p1 >> 16); }
;     __syncthreads();
;     constexpr int I_IN = 16 * (NPROJ / 32);
;     const int nitems = (G == 256) ? I_IN : I_IN + P0_REST_ITEMS;
;     for (int it = gw; it < nitems; it += NGW) {
;         if (it < I_IN) { const int nblk = NPROJ / 32, kb = it / nblk, nb = it % nblk, d = 32 * nb; int src, nv;
;             if (d < 3072) { src = d; nv = 32; } else { src = d + 16; nv = 32; }
;             transpose_item(P.w_in, 6672, 1024, (bf16_t*)(P.ws + WS_WIN), d, src, nv, nullptr, 64 * kb, scr, lane); continue; }
.LBB0_6:
	v_and_b32_e32 v7, 12, v5
	v_mad_u32_u24 v7, v7, s3, v6
	v_add_u32_e32 v40, 0xffffe7d0, v7
	global_load_dwordx4 v[8:11], v[2:3], off
	v_lshl_add_u64 v[2:3], v[2:3], 0, s[6:7]
	global_load_dwordx4 v[12:15], v[2:3], off
	v_lshl_add_u64 v[2:3], v[2:3], 0, s[6:7]
	global_load_dwordx4 v[16:19], v[2:3], off
	v_lshl_add_u64 v[2:3], v[2:3], 0, s[6:7]
	global_load_dwordx4 v[20:23], v[2:3], off
	v_lshl_add_u64 v[2:3], v[2:3], 0, s[6:7]
	global_load_dwordx4 v[24:27], v[2:3], off
	v_lshl_add_u64 v[2:3], v[2:3], 0, s[6:7]
	global_load_dwordx4 v[28:31], v[2:3], off
	v_lshl_add_u64 v[2:3], v[2:3], 0, s[6:7]
	global_load_dwordx4 v[32:35], v[2:3], off
	v_lshl_add_u64 v[2:3], v[2:3], 0, s[6:7]
	global_load_dwordx4 v[36:39], v[2:3], off
	s_waitcnt vmcnt(7)
	v_cvt_pk_bf16_f32 v8, v8, v9
	v_cvt_pk_bf16_f32 v9, v10, v11
	ds_write_b16 v40, v8 offset:0
	ds_write_b16_d16_hi v40, v8 offset:2064
	ds_write_b16 v40, v9 offset:4128
	ds_write_b16_d16_hi v40, v9 offset:6192
	s_waitcnt vmcnt(6)
	v_cvt_pk_bf16_f32 v12, v12, v13
	v_cvt_pk_bf16_f32 v13, v14, v15
	ds_write_b16 v40, v12 offset:256
	ds_write_b16_d16_hi v40, v12 offset:2320
	ds_write_b16 v40, v13 offset:4384
	ds_write_b16_d16_hi v40, v13 offset:6448
	s_waitcnt vmcnt(5)
	v_cvt_pk_bf16_f32 v16, v16, v17
	v_cvt_pk_bf16_f32 v17, v18, v19
	ds_write_b16 v40, v16 offset:512
	ds_write_b16_d16_hi v40, v16 offset:2576
	ds_write_b16 v40, v17 offset:4640
	ds_write_b16_d16_hi v40, v17 offset:6704
	s_waitcnt vmcnt(4)
	v_cvt_pk_bf16_f32 v20, v20, v21
	v_cvt_pk_bf16_f32 v21, v22, v23
	ds_write_b16 v40, v20 offset:768
	ds_write_b16_d16_hi v40, v20 offset:2832
	ds_write_b16 v40, v21 offset:4896
	ds_write_b16_d16_hi v40, v21 offset:6960
	s_waitcnt vmcnt(3)
	v_cvt_pk_bf16_f32 v24, v24, v25
	v_cvt_pk_bf16_f32 v25, v26, v27
	ds_write_b16 v40, v24 offset:1024
	ds_write_b16_d16_hi v40, v24 offset:3088
	ds_write_b16 v40, v25 offset:5152
	ds_write_b16_d16_hi v40, v25 offset:7216
	s_waitcnt vmcnt(2)
	v_cvt_pk_bf16_f32 v28, v28, v29
	v_cvt_pk_bf16_f32 v29, v30, v31
	ds_write_b16 v40, v28 offset:1280
	ds_write_b16_d16_hi v40, v28 offset:3344
	ds_write_b16 v40, v29 offset:5408
	ds_write_b16_d16_hi v40, v29 offset:7472
	s_waitcnt vmcnt(1)
	v_cvt_pk_bf16_f32 v32, v32, v33
	v_cvt_pk_bf16_f32 v33, v34, v35
	ds_write_b16 v40, v32 offset:1536
	ds_write_b16_d16_hi v40, v32 offset:3600
	ds_write_b16 v40, v33 offset:5664
	ds_write_b16_d16_hi v40, v33 offset:7728
	s_waitcnt vmcnt(0)
	v_cvt_pk_bf16_f32 v36, v36, v37
	v_cvt_pk_bf16_f32 v37, v38, v39
	ds_write_b16 v40, v36 offset:1792
	ds_write_b16_d16_hi v40, v36 offset:3856
	ds_write_b16 v40, v37 offset:5920
	ds_write_b16_d16_hi v40, v37 offset:7984
	s_or_b64 exec, exec, s[0:1]
	s_lshl_b32 s33, s2, 3
	v_lshrrev_b32_e32 v2, 6, v204
	s_movk_i32 s0, 0x3000
	s_cmpk_eq_i32 s70, 0x100
	v_mad_u32_u24 v61, v2, s0, 0
	s_cselect_b64 s[0:1], -1, 0
	v_writelane_b32 v246, s0, 5
	s_movk_i32 s3, 0xd00
	v_add_u32_e32 v64, s33, v2
	v_writelane_b32 v246, s1, 6
	s_and_b64 s[0:1], s[0:1], exec
	s_cselect_b32 s3, s3, 0x2300
	s_add_u32 s0, s68, 0x1e00000
	s_addc_u32 s1, s69, 0
	v_writelane_b32 v246, s0, 7
	s_waitcnt lgkmcnt(0)
	s_cmp_lg_u64 s[44:45], 0
	s_cselect_b64 s[6:7], -1, 0
	v_writelane_b32 v246, s1, 8
	v_writelane_b32 v246, s6, 9
	v_and_b32_e32 v63, 63, v204
	s_mov_b64 s[0:1], 0
	v_writelane_b32 v246, s7, 10
	s_add_u32 s6, s68, 0x1400000
	s_addc_u32 s7, s69, 0
	s_add_u32 s72, s68, 0x1200000
	s_addc_u32 s73, s69, 0
	s_add_u32 s76, s68, 0x1000000
	s_addc_u32 s77, s69, 0
	s_add_u32 s14, s68, 0x200000
	v_writelane_b32 v246, s6, 11
	s_addc_u32 s15, s69, 0
	v_cmp_gt_i32_e32 vcc, s3, v64
	v_writelane_b32 v246, s7, 12
	s_add_u32 s6, s68, 0x1600000
	s_addc_u32 s7, s69, 0
	v_writelane_b32 v246, s6, 13
	s_barrier
	s_nop 0
	v_writelane_b32 v246, s7, 14
	s_and_saveexec_b64 s[6:7], vcc
	s_cbranch_execz .LBB0_32
	v_and_b32_e32 v2, 7, v204
	v_readlane_b32 s10, v246, 13
	v_lshlrev_b32_e32 v34, 4, v2
	v_mov_b32_e32 v35, 0
	v_readlane_b32 s11, v246, 14
	v_lshrrev_b32_e32 v65, 3, v63
	v_add_u32_e32 v3, v61, v34
	v_lshl_add_u64 v[42:43], s[10:11], 0, v[34:35]
	v_readlane_b32 s10, v246, 11
	v_readlane_b32 s11, v246, 12
	v_mul_u32_u24_e32 v4, 0x84, v65
	v_mul_u32_u24_e32 v2, 0x420, v2
	v_lshl_add_u64 v[44:45], s[10:11], 0, v[34:35]
	v_lshlrev_b32_e32 v5, 2, v65
	v_readlane_b32 s10, v246, 7
	v_add3_u32 v69, v61, v2, v5
	v_readlane_b32 s11, v246, 8
	v_mov_b32_e32 v2, 0xffffe600
	v_add_u32_e32 v71, v3, v4
	s_lshl_b32 s8, s70, 3
	v_lshl_add_u64 v[36:37], s[46:47], 0, v[34:35]
	v_lshl_add_u64 v[38:39], s[40:41], 0, v[34:35]
	v_lshl_add_u64 v[40:41], s[56:57], 0, v[34:35]
	v_lshl_add_u64 v[46:47], s[72:73], 0, v[34:35]
	v_lshl_add_u64 v[48:49], s[76:77], 0, v[34:35]
	v_lshl_add_u64 v[50:51], s[14:15], 0, v[34:35]
	v_or_b32_e32 v66, 8, v65
	v_or_b32_e32 v67, 16, v65
	v_or_b32_e32 v68, 24, v65
	v_lshl_add_u64 v[52:53], s[48:49], 0, v[34:35]
	v_lshl_add_u64 v[54:55], s[42:43], 0, v[34:35]
	v_lshl_add_u64 v[56:57], s[38:39], 0, v[34:35]
	v_lshl_add_u64 v[58:59], s[10:11], 0, v[34:35]
	v_lshlrev_b32_e32 v60, 5, v64
	s_lshl_b32 s9, s70, 8
	s_movk_i32 s10, 0xe600
	v_lshl_add_u32 v70, v64, 1, v2
	s_lshl_b32 s11, s70, 4
	s_movk_i32 s12, 0xcff
	s_movk_i32 s13, 0x1ff
	s_movk_i32 s26, 0x3ff
	s_movk_i32 s27, 0x5ff
	s_movk_i32 s28, 0xdff
	v_add_u32_e32 v72, 0x420, v71
	v_add_u32_e32 v73, 0x428, v71
	v_add_u32_e32 v74, 0x840, v71
	v_add_u32_e32 v75, 0x848, v71
	v_add_u32_e32 v76, 0xc60, v71
	v_add_u32_e32 v77, 0xc68, v71
	v_add_u32_e32 v78, 0x1080, v71
	v_add_u32_e32 v79, 0x1088, v71
	v_add_u32_e32 v80, 0x14a0, v71
	v_add_u32_e32 v81, 0x14a8, v71
	v_add_u32_e32 v82, 0x18c0, v71
	v_add_u32_e32 v83, 0x18c8, v71
	v_add_u32_e32 v84, 0x1ce0, v71
	s_mov_b32 s29, 0x4ec4ec4f
	s_movk_i32 s30, 0xff30
	s_movk_i32 s31, 0x60
	s_movk_i32 s34, 0x6840
	v_add_u32_e32 v85, 0x1ce8, v71
	v_mov_b32_e32 v62, v64
	s_branch .LBB0_10
